# prologue fp6 weight items: next item's 16 loads prefetched into spare registers once the current item's loads have arrived
# baseline (speedup 1.0000x reference)
.LBB0_16:
	s_or_b64 exec, exec, s[4:5]
	s_mul_i32 s4, s78, 0x4400
	s_add_i32 s18, s4, 0
	v_readlane_b32 s4, v249, 34
	v_readfirstlane_b32 s53, v2
	s_lshl_b32 s4, s4, 3
	s_lshr_b32 s6, s53, 3
	s_lshl_b32 s9, s76, 3
	s_mul_i32 s6, s6, s4
	v_readlane_b32 s5, v249, 35
	s_add_i32 s6, s6, s9
	s_and_b32 s8, s53, 7
	s_ashr_i32 s5, s4, 31
	s_or_b32 s52, s6, s8
	s_mov_b32 s7, 0
	v_lshrrev_b32_e32 v67, 3, v178
	v_and_b32_e32 v1, 7, v0
	v_lshlrev_b32_e32 v66, 4, v0
	s_cmp_gt_i32 s52, 0x196ff
	v_and_b32_e32 v76, 3, v0
	s_cbranch_scc1 .LBB0_51
	s_add_u32 s19, s92, 0x200000
	s_addc_u32 s20, s93, 0
	s_add_u32 s21, s92, 0x7000000
	v_lshrrev_b32_e32 v9, 4, v178
	v_and_b32_e32 v10, 15, v0
	s_addc_u32 s22, s93, 0
	v_mul_u32_u24_e32 v11, 0x1080, v9
	v_lshlrev_b32_e32 v70, 7, v9
	v_lshlrev_b32_e32 v9, 2, v10
	s_add_u32 s23, s92, 0x3000000
	v_add3_u32 v86, s18, v11, v9
	v_lshrrev_b32_e32 v9, 1, v0
	s_addc_u32 s24, s93, 0
	v_and_b32_e32 v12, 48, v0
	v_and_or_b32 v9, v9, 4, v76
	s_add_u32 s25, s92, 0x1000000
	v_mul_u32_u24_e32 v5, 0x420, v1
	v_lshlrev_b32_e32 v6, 2, v67
	v_lshl_or_b32 v72, v9, 6, v12
	v_lshlrev_b32_e32 v87, 3, v9
	v_or_b32_e32 v9, 16, v10
	s_addc_u32 s26, s93, 0
	v_add3_u32 v81, s18, v5, v6
	v_and_b32_e32 v5, 48, v66
	v_lshlrev_b32_e32 v7, 6, v67
	s_movk_i32 s8, 0x100
	v_lshrrev_b32_e32 v9, 1, v9
	s_add_u32 s27, s92, 0x20000000
	v_lshl_add_u32 v3, v1, 4, s18
	v_mul_u32_u24_e32 v4, 0x84, v67
	v_and_b32_e32 v8, 0xc0, v7
	v_or3_b32 v84, v7, v5, s8
	v_and_b32_e32 v7, 28, v179
	v_and_or_b32 v9, v9, 12, v76
	s_addc_u32 s28, s93, 0
	v_lshlrev_b32_e32 v2, 3, v1
	v_mov_b32_e32 v69, 0
	v_or_b32_e32 v85, 0x1400, v7
	v_lshl_add_u32 v7, v7, 2, s18
	v_lshlrev_b32_e32 v10, 6, v9
	s_add_u32 s29, s92, 0x5d800000
	v_add_u32_e32 v91, v3, v4
	v_lshlrev_b32_e32 v77, 2, v1
	v_or_b32_e32 v78, 8, v67
	v_or_b32_e32 v79, 16, v67
	v_or_b32_e32 v80, 24, v67
	v_lshrrev_b32_e32 v82, 2, v1
	v_or_b32_e32 v83, v8, v5
	v_mov_b32_e32 v71, v69
	v_mov_b32_e32 v73, v69
	v_bitop3_b32 v74, v10, 32, v12 bitop3:0x36
	v_mov_b32_e32 v75, v69
	v_lshlrev_b32_e32 v88, 3, v9
	v_and_b32_e32 v89, 16, v6
	s_addc_u32 s30, s93, 0
	v_bitop3_b32 v90, v8, 32, v5 bitop3:0x36
	s_add_i32 s31, 0, 0x22980
	v_add_u32_e32 v92, 0x420, v91
	v_add_u32_e32 v93, 0x428, v91
	v_add_u32_e32 v94, 0x840, v91
	v_add_u32_e32 v95, 0x848, v91
	v_add_u32_e32 v96, 0xc60, v91
	v_add_u32_e32 v97, 0xc68, v91
	v_add_u32_e32 v98, 0x1080, v91
	v_add_u32_e32 v99, 0x1088, v91
	v_add_u32_e32 v100, 0x14a0, v91
	v_add_u32_e32 v101, 0x14a8, v91
	v_add_u32_e32 v102, 0x18c0, v91
	s_mov_b32 s33, 0x20000
	s_mov_b32 s34, 0x40000
	s_mov_b32 s35, 0x60000
	s_mov_b32 s36, 0x80000
	s_mov_b32 s37, 0xa0000
	s_mov_b32 s38, 0xc0000
	s_mov_b32 s39, 0xe0000
	s_mov_b32 s40, 0x25e000
	s_mov_b32 s41, 0x194000
	s_mov_b32 s42, 0xca000
	s_mov_b32 s8, 0x43000000
	v_add_u32_e32 v103, v7, v4
	s_mov_b32 s43, 0x651000
	s_mov_b32 s44, 0x71b000
	s_mov_b32 s45, 0x7e5000
	s_mov_b32 s46, 0x8af000
	s_mov_b32 s47, 0x979000
	s_mov_b32 s48, 0xa43000
	s_mov_b32 s49, 0xb0d000
	s_mov_b32 s50, 0xbd7000
	s_mov_b64 s[10:11], 0x2000
	v_add_u32_e32 v104, 0x18c8, v91
	v_add_u32_e32 v105, 0x1ce0, v91
	v_add_u32_e32 v106, 0x1ce8, v91
	v_lshlrev_b32_e32 v68, 1, v2
	v_mov_b32_e32 v107, 0x3000
	s_mov_b32 s77, 0
	s_branch .LBB0_19

.LBB0_49:
	s_andn2_b64 vcc, exec, s[12:13]
	s_cbranch_vccnz .LBB0_18
	s_cmp_eq_u32 s77, 1
	s_cbranch_scc1 .Lpf_use
	s_mul_hi_i32 s6, s52, 0x1948b0fd
	s_lshr_b32 s12, s6, 31
	s_ashr_i32 s6, s6, 11
	s_add_i32 s12, s6, s12
	s_mul_i32 s6, s12, 0xffffaf00
	s_add_i32 s13, s6, s52
	s_mul_hi_i32 s6, s13, 0x1948b0fd
	s_lshr_b32 s14, s6, 31
	s_ashr_i32 s6, s6, 6
	s_add_i32 s6, s6, s14
	s_mul_i32 s14, s6, 0x288
	v_readlane_b32 s52, v249, 0
	s_sub_i32 s14, s13, s14
	s_mul_i32 s15, s12, 0x19440000
	v_readlane_b32 s58, v249, 6
	s_mul_hi_i32 s13, s12, 0x19440000
	v_readlane_b32 s59, v249, 7
	s_add_u32 s16, s58, s15
	s_addc_u32 s17, s59, s13
	s_mul_hi_i32 s13, s12, 0x3cc0000
	s_mul_i32 s12, s12, 0x3cc0000
	s_add_u32 s12, s29, s12
	s_addc_u32 s13, s30, s13
	s_lshl_b32 s15, s14, 5
	v_add_u32_e32 v2, s15, v85
	s_movk_i32 s52, 0x1400
	v_add_u32_e32 v3, 16, v2
	v_cmp_gt_i32_e32 vcc, s52, v2
	v_mov_b64_e32 v[4:5], s[16:17]
	s_mov_b32 s16, 0x19440
	v_cndmask_b32_e32 v2, v3, v2, vcc
	v_lshl_or_b32 v3, s6, 7, v67
	v_mad_i64_i32 v[4:5], s[16:17], v3, s16, v[4:5]
	v_ashrrev_i32_e32 v3, 31, v2
	v_lshl_add_u64 v[58:59], v[2:3], 2, v[4:5]
	global_load_dwordx4 v[2:5], v[58:59], off
	v_add_co_u32_e32 v6, vcc, s42, v58
	s_mov_b32 s16, 0x328000
	s_nop 0
	v_addc_co_u32_e32 v7, vcc, 0, v59, vcc
	global_load_dwordx4 v[6:9], v[6:7], off offset:512
	v_add_co_u32_e32 v10, vcc, s41, v58
	v_add_u32_e32 v108, 0x420, v103
	s_nop 0
	v_addc_co_u32_e32 v11, vcc, 0, v59, vcc
	v_add_co_u32_e32 v14, vcc, s40, v58
	global_load_dwordx4 v[10:13], v[10:11], off offset:1024
	s_nop 0
	v_addc_co_u32_e32 v15, vcc, 0, v59, vcc
	v_add_co_u32_e32 v18, vcc, s16, v58
	global_load_dwordx4 v[14:17], v[14:15], off offset:1536
	s_nop 0
	v_addc_co_u32_e32 v19, vcc, 0, v59, vcc
	s_mov_b32 s16, 0x3f2000
	v_add_co_u32_e32 v22, vcc, s16, v58
	global_load_dwordx4 v[18:21], v[18:19], off offset:2048
	s_nop 0
	v_addc_co_u32_e32 v23, vcc, 0, v59, vcc
	s_mov_b32 s16, 0x4bc000
	v_add_co_u32_e32 v26, vcc, s16, v58
	global_load_dwordx4 v[22:25], v[22:23], off offset:2560
	s_nop 0
	v_addc_co_u32_e32 v27, vcc, 0, v59, vcc
	s_mov_b32 s16, 0x586000
	v_add_co_u32_e32 v30, vcc, s16, v58
	global_load_dwordx4 v[26:29], v[26:27], off offset:3072
	s_nop 0
	v_addc_co_u32_e32 v31, vcc, 0, v59, vcc
	v_add_co_u32_e32 v34, vcc, s43, v58
	global_load_dwordx4 v[30:33], v[30:31], off offset:3584
	s_nop 0
	v_addc_co_u32_e32 v35, vcc, 0, v59, vcc
	v_add_co_u32_e32 v38, vcc, s44, v58
	global_load_dwordx4 v[34:37], v[34:35], off
	s_nop 0
	v_addc_co_u32_e32 v39, vcc, 0, v59, vcc
	v_add_co_u32_e32 v42, vcc, s45, v58
	global_load_dwordx4 v[38:41], v[38:39], off offset:512
	s_nop 0
	v_addc_co_u32_e32 v43, vcc, 0, v59, vcc
	v_add_co_u32_e32 v46, vcc, s46, v58
	global_load_dwordx4 v[42:45], v[42:43], off offset:1024
	s_nop 0
	v_addc_co_u32_e32 v47, vcc, 0, v59, vcc
	v_add_co_u32_e32 v50, vcc, s47, v58
	global_load_dwordx4 v[46:49], v[46:47], off offset:1536
	s_nop 0
	v_addc_co_u32_e32 v51, vcc, 0, v59, vcc
	global_load_dwordx4 v[50:53], v[50:51], off offset:2048
	v_add_u32_e32 v109, 0x428, v103
	v_add_u32_e32 v110, 0x840, v103
	v_add_u32_e32 v111, 0x848, v103
	s_ashr_i32 s14, s14, 2
	s_and_b32 s17, s15, 0x60
	s_ashr_i32 s15, s14, 31
	s_ashr_i32 s16, s6, 31
	s_lshl_b64 s[14:15], s[14:15], 5
	s_add_u32 s6, s14, s6
	s_addc_u32 s14, s15, s16
	s_mul_i32 s16, s14, 0x3000
	s_mul_hi_u32 s14, s6, 0x3000
	s_add_i32 s15, s14, s16
	s_mul_i32 s14, s6, 0x3000
	s_waitcnt vmcnt(12)
	v_pk_mul_f32 v[2:3], v[2:3], s[8:9] op_sel_hi:[1,0]
	ds_write2_b32 v103, v2, v3 offset1:1
	v_add_co_u32_e32 v2, vcc, s48, v58
	v_pk_mul_f32 v[60:61], v[4:5], s[8:9] op_sel_hi:[1,0]
	s_nop 0
	v_addc_co_u32_e32 v3, vcc, 0, v59, vcc
	global_load_dwordx4 v[2:5], v[2:3], off offset:2560
	s_waitcnt vmcnt(12)
	v_pk_mul_f32 v[62:63], v[6:7], s[8:9] op_sel_hi:[1,0]
	v_add_co_u32_e32 v6, vcc, s49, v58
	v_pk_mul_f32 v[64:65], v[8:9], s[8:9] op_sel_hi:[1,0]
	s_nop 0
	v_addc_co_u32_e32 v7, vcc, 0, v59, vcc
	global_load_dwordx4 v[54:57], v[6:7], off offset:3072
	v_add_co_u32_e32 v6, vcc, s50, v58
	s_waitcnt vmcnt(12)
	v_pk_mul_f32 v[10:11], v[10:11], s[8:9] op_sel_hi:[1,0]
	v_addc_co_u32_e32 v7, vcc, 0, v59, vcc
	global_load_dwordx4 v[6:9], v[6:7], off offset:3584
	v_pk_mul_f32 v[12:13], v[12:13], s[8:9] op_sel_hi:[1,0]
	ds_write2_b32 v108, v62, v63 offset1:1
	ds_write2_b32 v109, v64, v65 offset1:1
	ds_write2_b32 v110, v10, v11 offset1:1
	ds_write2_b32 v111, v12, v13 offset1:1
	s_waitcnt vmcnt(12)
	v_pk_mul_f32 v[10:11], v[14:15], s[8:9] op_sel_hi:[1,0]
	v_add_u32_e32 v12, 0xc60, v103
	ds_write2_b32 v12, v10, v11 offset1:1
	ds_write2_b32 v103, v60, v61 offset0:2 offset1:3
	v_pk_mul_f32 v[10:11], v[16:17], s[8:9] op_sel_hi:[1,0]
	v_add_u32_e32 v12, 0xc68, v103
	ds_write2_b32 v12, v10, v11 offset1:1
	s_waitcnt vmcnt(11)
	v_pk_mul_f32 v[10:11], v[18:19], s[8:9] op_sel_hi:[1,0]
	v_add_u32_e32 v12, 0x1080, v103
	ds_write2_b32 v12, v10, v11 offset1:1
	v_pk_mul_f32 v[10:11], v[20:21], s[8:9] op_sel_hi:[1,0]
	v_add_u32_e32 v12, 0x1088, v103
	ds_write2_b32 v12, v10, v11 offset1:1
	s_waitcnt vmcnt(10)
	v_pk_mul_f32 v[10:11], v[22:23], s[8:9] op_sel_hi:[1,0]
	v_add_u32_e32 v12, 0x14a0, v103
	ds_write2_b32 v12, v10, v11 offset1:1
	v_pk_mul_f32 v[10:11], v[24:25], s[8:9] op_sel_hi:[1,0]
	v_add_u32_e32 v12, 0x14a8, v103
	ds_write2_b32 v12, v10, v11 offset1:1
	s_waitcnt vmcnt(9)
	v_pk_mul_f32 v[10:11], v[26:27], s[8:9] op_sel_hi:[1,0]
	v_add_u32_e32 v12, 0x18c0, v103
	ds_write2_b32 v12, v10, v11 offset1:1
	v_pk_mul_f32 v[10:11], v[28:29], s[8:9] op_sel_hi:[1,0]
	v_add_u32_e32 v12, 0x18c8, v103
	ds_write2_b32 v12, v10, v11 offset1:1
	s_waitcnt vmcnt(8)
	v_pk_mul_f32 v[10:11], v[30:31], s[8:9] op_sel_hi:[1,0]
	v_add_u32_e32 v12, 0x1ce0, v103
	ds_write2_b32 v12, v10, v11 offset1:1
	v_pk_mul_f32 v[10:11], v[32:33], s[8:9] op_sel_hi:[1,0]
	v_add_u32_e32 v12, 0x1ce8, v103
	ds_write2_b32 v12, v10, v11 offset1:1
	s_waitcnt vmcnt(7)
	v_pk_mul_f32 v[10:11], v[34:35], s[8:9] op_sel_hi:[1,0]
	v_add_u32_e32 v12, 0x2100, v103
	ds_write2_b32 v12, v10, v11 offset1:1
	v_pk_mul_f32 v[10:11], v[36:37], s[8:9] op_sel_hi:[1,0]
	v_add_u32_e32 v12, 0x2108, v103
	ds_write2_b32 v12, v10, v11 offset1:1
	s_waitcnt vmcnt(6)
	v_pk_mul_f32 v[10:11], v[38:39], s[8:9] op_sel_hi:[1,0]
	v_add_u32_e32 v12, 0x2520, v103
	ds_write2_b32 v12, v10, v11 offset1:1
	v_pk_mul_f32 v[10:11], v[40:41], s[8:9] op_sel_hi:[1,0]
	v_add_u32_e32 v12, 0x2528, v103
	ds_write2_b32 v12, v10, v11 offset1:1
	s_waitcnt vmcnt(5)
	v_pk_mul_f32 v[10:11], v[42:43], s[8:9] op_sel_hi:[1,0]
	v_add_u32_e32 v12, 0x2940, v103
	ds_write2_b32 v12, v10, v11 offset1:1
	v_pk_mul_f32 v[10:11], v[44:45], s[8:9] op_sel_hi:[1,0]
	v_add_u32_e32 v12, 0x2948, v103
	ds_write2_b32 v12, v10, v11 offset1:1
	s_waitcnt vmcnt(4)
	v_pk_mul_f32 v[10:11], v[46:47], s[8:9] op_sel_hi:[1,0]
	v_add_u32_e32 v12, 0x2d60, v103
	ds_write2_b32 v12, v10, v11 offset1:1
	v_pk_mul_f32 v[10:11], v[48:49], s[8:9] op_sel_hi:[1,0]
	v_add_u32_e32 v12, 0x2d68, v103
	ds_write2_b32 v12, v10, v11 offset1:1
	s_waitcnt vmcnt(3)
	v_pk_mul_f32 v[10:11], v[50:51], s[8:9] op_sel_hi:[1,0]
	v_add_u32_e32 v12, 0x3180, v103
	ds_write2_b32 v12, v10, v11 offset1:1
	v_pk_mul_f32 v[10:11], v[52:53], s[8:9] op_sel_hi:[1,0]
	v_add_u32_e32 v12, 0x3188, v103
	ds_write2_b32 v12, v10, v11 offset1:1
	v_add_u32_e32 v10, 0x35a0, v103
	v_add_u32_e32 v45, 0x400, v86
	v_add_u32_e32 v53, 0x800, v86
	v_add_u32_e32 v24, 0xa00, v86
	s_waitcnt vmcnt(2)
	v_pk_mul_f32 v[2:3], v[2:3], s[8:9] op_sel_hi:[1,0]
	ds_write2_b32 v10, v2, v3 offset1:1
	v_pk_mul_f32 v[2:3], v[4:5], s[8:9] op_sel_hi:[1,0]
	v_add_u32_e32 v4, 0x35a8, v103
	ds_write2_b32 v4, v2, v3 offset1:1
	v_add_u32_e32 v4, 0x39c0, v103
	v_add_u32_e32 v60, 0xc00, v86
	s_waitcnt vmcnt(1)
	v_pk_mul_f32 v[2:3], v[54:55], s[8:9] op_sel_hi:[1,0]
	ds_write2_b32 v4, v2, v3 offset1:1
	v_pk_mul_f32 v[2:3], v[56:57], s[8:9] op_sel_hi:[1,0]
	v_add_u32_e32 v4, 0x39c8, v103
	ds_write2_b32 v4, v2, v3 offset1:1
	v_add_u32_e32 v4, 0x3de0, v103
	s_waitcnt vmcnt(0)
.Lpf_join:
	s_ashr_i32 s72, s51, 3
	s_mul_i32 s72, s72, s4
	s_add_i32 s72, s72, s9
	s_and_b32 s73, s51, 7
	s_or_b32 s72, s72, s73
	s_cmp_gt_i32 s72, 0xa1ff
	s_cbranch_scc1 .Lpf_skip
	s_mul_hi_i32 s73, s72, 0x1948b0fd
	s_lshr_b32 s74, s73, 31
	s_ashr_i32 s73, s73, 11
	s_add_i32 s74, s73, s74
	s_mul_i32 s73, s74, 0xffffaf00
	s_add_i32 s79, s73, s72
	s_mul_hi_i32 s73, s79, 0x1948b0fd
	s_lshr_b32 s80, s73, 31
	s_ashr_i32 s73, s73, 6
	s_add_i32 s73, s73, s80
	s_mul_i32 s80, s73, 0x288
	s_sub_i32 s80, s79, s80
	v_readlane_b32 s84, v249, 6
	v_readlane_b32 s85, v249, 7
	s_mul_i32 s81, s74, 0x19440000
	s_mul_hi_i32 s82, s74, 0x19440000
	s_lshl_b32 s80, s80, 5
	s_nop 0
	s_add_u32 s84, s84, s81
	s_addc_u32 s85, s85, s82
	v_add_u32_e32 v212, s80, v85
	v_add_u32_e32 v213, 16, v212
	s_movk_i32 s82, 0x1400
	v_cmp_gt_i32_e32 vcc, s82, v212
	v_mov_b64_e32 v[214:215], s[84:85]
	s_mov_b32 s86, 0x19440
	v_cndmask_b32_e32 v212, v213, v212, vcc
	v_lshl_or_b32 v213, s73, 7, v67
	v_mad_i64_i32 v[214:215], s[86:87], v213, s86, v[214:215]
	v_ashrrev_i32_e32 v213, 31, v212
	v_lshl_add_u64 v[216:217], v[212:213], 2, v[214:215]
	global_load_dwordx4 v[140:143], v[216:217], off
	v_add_co_u32_e32 v218, vcc, s42, v216
	s_nop 0
	v_addc_co_u32_e32 v219, vcc, 0, v217, vcc
	global_load_dwordx4 v[144:147], v[218:219], off offset:512
	v_add_co_u32_e32 v218, vcc, s41, v216
	s_nop 0
	v_addc_co_u32_e32 v219, vcc, 0, v217, vcc
	global_load_dwordx4 v[148:151], v[218:219], off offset:1024
	v_add_co_u32_e32 v218, vcc, s40, v216
	s_nop 0
	v_addc_co_u32_e32 v219, vcc, 0, v217, vcc
	global_load_dwordx4 v[152:155], v[218:219], off offset:1536
	s_mov_b32 s81, 0x328000
	v_add_co_u32_e32 v218, vcc, s81, v216
	s_nop 0
	v_addc_co_u32_e32 v219, vcc, 0, v217, vcc
	global_load_dwordx4 v[156:159], v[218:219], off offset:2048
	s_mov_b32 s81, 0x3f2000
	v_add_co_u32_e32 v218, vcc, s81, v216
	s_nop 0
	v_addc_co_u32_e32 v219, vcc, 0, v217, vcc
	global_load_dwordx4 v[160:163], v[218:219], off offset:2560
	s_mov_b32 s81, 0x4bc000
	v_add_co_u32_e32 v218, vcc, s81, v216
	s_nop 0
	v_addc_co_u32_e32 v219, vcc, 0, v217, vcc
	global_load_dwordx4 v[164:167], v[218:219], off offset:3072
	s_mov_b32 s81, 0x586000
	v_add_co_u32_e32 v218, vcc, s81, v216
	s_nop 0
	v_addc_co_u32_e32 v219, vcc, 0, v217, vcc
	global_load_dwordx4 v[168:171], v[218:219], off offset:3584
	v_add_co_u32_e32 v218, vcc, s43, v216
	s_nop 0
	v_addc_co_u32_e32 v219, vcc, 0, v217, vcc
	global_load_dwordx4 v[172:175], v[218:219], off
	v_add_co_u32_e32 v218, vcc, s44, v216
	s_nop 0
	v_addc_co_u32_e32 v219, vcc, 0, v217, vcc
	global_load_dwordx4 v[180:183], v[218:219], off offset:512
	v_add_co_u32_e32 v218, vcc, s45, v216
	s_nop 0
	v_addc_co_u32_e32 v219, vcc, 0, v217, vcc
	global_load_dwordx4 v[184:187], v[218:219], off offset:1024
	v_add_co_u32_e32 v218, vcc, s46, v216
	s_nop 0
	v_addc_co_u32_e32 v219, vcc, 0, v217, vcc
	global_load_dwordx4 v[188:191], v[218:219], off offset:1536
	v_add_co_u32_e32 v218, vcc, s47, v216
	s_nop 0
	v_addc_co_u32_e32 v219, vcc, 0, v217, vcc
	global_load_dwordx4 v[196:199], v[218:219], off offset:2048
	v_add_co_u32_e32 v218, vcc, s48, v216
	s_nop 0
	v_addc_co_u32_e32 v219, vcc, 0, v217, vcc
	global_load_dwordx4 v[200:203], v[218:219], off offset:2560
	v_add_co_u32_e32 v218, vcc, s49, v216
	s_nop 0
	v_addc_co_u32_e32 v219, vcc, 0, v217, vcc
	global_load_dwordx4 v[204:207], v[218:219], off offset:3072
	v_add_co_u32_e32 v218, vcc, s50, v216
	s_nop 0
	v_addc_co_u32_e32 v219, vcc, 0, v217, vcc
	global_load_dwordx4 v[208:211], v[218:219], off offset:3584
	s_mov_b32 s77, 1
.Lpf_skip:
	v_pk_mul_f32 v[2:3], v[6:7], s[8:9] op_sel_hi:[1,0]
	ds_write2_b32 v4, v2, v3 offset1:1
	v_pk_mul_f32 v[2:3], v[8:9], s[8:9] op_sel_hi:[1,0]
	v_add_u32_e32 v4, 0x3de8, v103
	ds_write2_b32 v4, v2, v3 offset1:1
	s_waitcnt lgkmcnt(0)
	v_add_u32_e32 v32, 0xe00, v86
	ds_read2_b32 v[108:109], v86 offset1:16
	ds_read2_b32 v[2:3], v86 offset0:33 offset1:49
	ds_read2_b32 v[4:5], v86 offset0:99 offset1:115
	ds_read2_b32 v[6:7], v86 offset0:165 offset1:181
	ds_read2_b32 v[8:9], v86 offset0:231 offset1:247
	ds_read2_b32 v[10:11], v45 offset0:41 offset1:57
	ds_read2_b32 v[12:13], v45 offset0:107 offset1:123
	ds_read2_b32 v[14:15], v45 offset0:173 offset1:189
	ds_read2_b32 v[16:17], v45 offset0:239 offset1:255
	ds_read2_b32 v[18:19], v53 offset0:49 offset1:65
	ds_read2_b32 v[20:21], v53 offset0:115 offset1:131
	ds_read2_b32 v[22:23], v53 offset0:181 offset1:197
	ds_read2_b32 v[24:25], v24 offset0:119 offset1:135
	ds_read2_b32 v[26:27], v60 offset0:57 offset1:73
	ds_read2_b32 v[28:29], v60 offset0:123 offset1:139
	ds_read2_b32 v[30:31], v60 offset0:189 offset1:205
	ds_read2_b32 v[110:111], v86 offset0:66 offset1:82
	ds_read2_b32 v[32:33], v32 offset0:127 offset1:143
	ds_read2_b32 v[112:113], v86 offset0:132 offset1:148
	ds_read2_b32 v[114:115], v86 offset0:198 offset1:214
	ds_read2_b32 v[116:117], v45 offset0:8 offset1:24
	ds_read2_b32 v[118:119], v45 offset0:74 offset1:90
	ds_read2_b32 v[120:121], v45 offset0:140 offset1:156
	ds_read2_b32 v[122:123], v45 offset0:206 offset1:222
	ds_read2_b32 v[124:125], v53 offset0:16 offset1:32
	ds_read2_b32 v[126:127], v53 offset0:82 offset1:98
	ds_read2_b32 v[128:129], v53 offset0:148 offset1:164
	ds_read2_b32 v[130:131], v53 offset0:214 offset1:230
	ds_read2_b32 v[132:133], v60 offset0:24 offset1:40
	ds_read2_b32 v[134:135], v60 offset0:90 offset1:106
	ds_read2_b32 v[136:137], v60 offset0:156 offset1:172
	ds_read2_b32 v[138:139], v60 offset0:222 offset1:238
	s_waitcnt lgkmcnt(14)
	v_mov_b32_e32 v34, v108
	v_mov_b32_e32 v35, v2
	v_mov_b32_e32 v36, v110
	v_mov_b32_e32 v37, v4
	s_waitcnt lgkmcnt(13)
	v_mov_b32_e32 v38, v112
	v_mov_b32_e32 v39, v6
	s_waitcnt lgkmcnt(12)
	v_mov_b32_e32 v40, v114
	v_mov_b32_e32 v41, v8
	s_waitcnt lgkmcnt(11)
	v_mov_b32_e32 v42, v116
	v_mov_b32_e32 v43, v10
	s_waitcnt lgkmcnt(10)
	v_mov_b32_e32 v44, v118
	v_mov_b32_e32 v45, v12
	s_waitcnt lgkmcnt(9)
	v_mov_b32_e32 v46, v120
	v_mov_b32_e32 v47, v14
	s_waitcnt lgkmcnt(8)
	v_mov_b32_e32 v48, v122
	v_mov_b32_e32 v49, v16
	s_waitcnt lgkmcnt(7)
	v_mov_b32_e32 v50, v124
	v_mov_b32_e32 v51, v18
	s_waitcnt lgkmcnt(6)
	v_mov_b32_e32 v52, v126
	v_mov_b32_e32 v53, v20
	s_waitcnt lgkmcnt(5)
	v_mov_b32_e32 v54, v128
	v_mov_b32_e32 v55, v22
	s_waitcnt lgkmcnt(4)
	v_mov_b32_e32 v56, v130
	v_mov_b32_e32 v57, v24
	s_waitcnt lgkmcnt(3)
	v_mov_b32_e32 v58, v132
	v_mov_b32_e32 v59, v26
	s_waitcnt lgkmcnt(2)
	v_mov_b32_e32 v60, v134
	v_mov_b32_e32 v61, v28
	s_waitcnt lgkmcnt(1)
	v_mov_b32_e32 v62, v136
	v_mov_b32_e32 v63, v30
	s_waitcnt lgkmcnt(0)
	v_mov_b32_e32 v64, v138
	v_mov_b32_e32 v65, v32
	v_and_or_b32 v2, v179, 16, s17
	s_add_u32 s14, s12, s14
	v_cvt_scalef32_2xpk16_fp6_f32 v[34:39], v[34:49], v[50:65], 1.0
	v_lshlrev_b32_e32 v40, 6, v2
	v_mov_b32_e32 v41, v69
	s_addc_u32 s15, s13, s15
	v_lshl_add_u64 v[40:41], s[14:15], 0, v[40:41]
	v_lshl_add_u64 v[42:43], v[40:41], 0, v[72:73]
	global_store_dwordx4 v[42:43], v[34:37], off
	v_mov_b32_e32 v4, v111
	v_mov_b32_e32 v6, v113
	v_lshlrev_b32_e32 v36, 5, v2
	v_mov_b32_e32 v2, v109
	v_mov_b32_e32 v8, v115
	v_mov_b32_e32 v10, v117
	v_mov_b32_e32 v12, v119
	v_mov_b32_e32 v14, v121
	v_mov_b32_e32 v16, v123
	v_mov_b32_e32 v18, v125
	v_mov_b32_e32 v20, v127
	v_mov_b32_e32 v22, v129
	v_mov_b32_e32 v24, v131
	v_mov_b32_e32 v26, v133
	v_mov_b32_e32 v28, v135
	v_mov_b32_e32 v30, v137
	v_mov_b32_e32 v32, v139
	v_or_b32_e32 v34, v36, v87
	v_mov_b32_e32 v35, v69
	v_cvt_scalef32_2xpk16_fp6_f32 v[2:7], v[2:17], v[18:33], 1.0
	v_or_b32_e32 v8, v36, v88
	v_lshl_add_u64 v[10:11], v[40:41], 0, v[74:75]
	v_mov_b32_e32 v9, v69
	v_lshl_add_u64 v[34:35], s[12:13], 0, v[34:35]
	global_store_dwordx4 v[10:11], v[2:5], off
	v_lshl_add_u64 v[34:35], v[34:35], 0, v[70:71]
	v_lshl_add_u64 v[34:35], v[34:35], 0, s[10:11]
	v_lshl_add_u64 v[2:3], s[12:13], 0, v[8:9]
	v_lshl_add_u64 v[2:3], v[2:3], 0, v[70:71]
	v_lshl_add_u64 v[2:3], v[2:3], 0, s[10:11]
	v_mad_u64_u32 v[34:35], s[14:15], s6, v107, v[34:35]
	v_mad_u64_u32 v[2:3], s[12:13], s6, v107, v[2:3]
	v_add_u32_e32 v35, s16, v35
	v_add_u32_e32 v3, s16, v3
	global_store_dwordx2 v[34:35], v[38:39], off
	global_store_dwordx2 v[2:3], v[6:7], off
	s_waitcnt lgkmcnt(0)
	v_readlane_b32 s53, v249, 1
	v_readlane_b32 s54, v249, 2
	v_readlane_b32 s55, v249, 3
	v_readlane_b32 s56, v249, 4
	v_readlane_b32 s57, v249, 5
	v_readlane_b32 s60, v249, 8
	v_readlane_b32 s61, v249, 9
	v_readlane_b32 s62, v249, 10
	v_readlane_b32 s63, v249, 11
	v_readlane_b32 s64, v249, 12
	v_readlane_b32 s65, v249, 13
	v_readlane_b32 s66, v249, 14
	v_readlane_b32 s67, v249, 15
	s_branch .LBB0_18
.Lpf_use:
	s_mov_b32 s77, 0
	s_waitcnt vmcnt(4)
	s_mul_hi_i32 s6, s52, 0x1948b0fd
	s_lshr_b32 s12, s6, 31
	s_ashr_i32 s6, s6, 11
	s_add_i32 s12, s6, s12
	s_mul_i32 s6, s12, 0xffffaf00
	s_add_i32 s13, s6, s52
	s_mul_hi_i32 s6, s13, 0x1948b0fd
	s_lshr_b32 s14, s6, 31
	s_ashr_i32 s6, s6, 6
	s_add_i32 s6, s6, s14
	s_mul_i32 s14, s6, 0x288
	v_readlane_b32 s52, v249, 0
	s_sub_i32 s14, s13, s14
	s_mul_i32 s15, s12, 0x19440000
	v_readlane_b32 s58, v249, 6
	s_mul_hi_i32 s13, s12, 0x19440000
	v_readlane_b32 s59, v249, 7
	s_add_u32 s16, s58, s15
	s_addc_u32 s17, s59, s13
	s_mul_hi_i32 s13, s12, 0x3cc0000
	s_mul_i32 s12, s12, 0x3cc0000
	s_add_u32 s12, s29, s12
	s_addc_u32 s13, s30, s13
	s_lshl_b32 s15, s14, 5
	v_add_u32_e32 v2, s15, v85
	s_movk_i32 s52, 0x1400
	v_add_u32_e32 v3, 16, v2
	v_cmp_gt_i32_e32 vcc, s52, v2
	v_mov_b64_e32 v[4:5], s[16:17]
	s_mov_b32 s16, 0x19440
	v_cndmask_b32_e32 v2, v3, v2, vcc
	v_lshl_or_b32 v3, s6, 7, v67
	v_mad_i64_i32 v[4:5], s[16:17], v3, s16, v[4:5]
	v_ashrrev_i32_e32 v3, 31, v2
	v_lshl_add_u64 v[58:59], v[2:3], 2, v[4:5]
	v_mov_b32_e32 v2, v140
	v_mov_b32_e32 v3, v141
	v_mov_b32_e32 v4, v142
	v_mov_b32_e32 v5, v143
	v_add_co_u32_e32 v6, vcc, s42, v58
	s_mov_b32 s16, 0x328000
	s_nop 0
	v_addc_co_u32_e32 v7, vcc, 0, v59, vcc
	v_mov_b32_e32 v6, v144
	v_mov_b32_e32 v7, v145
	v_mov_b32_e32 v8, v146
	v_mov_b32_e32 v9, v147
	v_add_co_u32_e32 v10, vcc, s41, v58
	v_add_u32_e32 v108, 0x420, v103
	s_nop 0
	v_addc_co_u32_e32 v11, vcc, 0, v59, vcc
	v_add_co_u32_e32 v14, vcc, s40, v58
	v_mov_b32_e32 v10, v148
	v_mov_b32_e32 v11, v149
	v_mov_b32_e32 v12, v150
	v_mov_b32_e32 v13, v151
	s_nop 0
	v_addc_co_u32_e32 v15, vcc, 0, v59, vcc
	v_add_co_u32_e32 v18, vcc, s16, v58
	v_mov_b32_e32 v14, v152
	v_mov_b32_e32 v15, v153
	v_mov_b32_e32 v16, v154
	v_mov_b32_e32 v17, v155
	s_nop 0
	v_addc_co_u32_e32 v19, vcc, 0, v59, vcc
	s_mov_b32 s16, 0x3f2000
	v_add_co_u32_e32 v22, vcc, s16, v58
	v_mov_b32_e32 v18, v156
	v_mov_b32_e32 v19, v157
	v_mov_b32_e32 v20, v158
	v_mov_b32_e32 v21, v159
	s_nop 0
	v_addc_co_u32_e32 v23, vcc, 0, v59, vcc
	s_mov_b32 s16, 0x4bc000
	v_add_co_u32_e32 v26, vcc, s16, v58
	v_mov_b32_e32 v22, v160
	v_mov_b32_e32 v23, v161
	v_mov_b32_e32 v24, v162
	v_mov_b32_e32 v25, v163
	s_nop 0
	v_addc_co_u32_e32 v27, vcc, 0, v59, vcc
	s_mov_b32 s16, 0x586000
	v_add_co_u32_e32 v30, vcc, s16, v58
	v_mov_b32_e32 v26, v164
	v_mov_b32_e32 v27, v165
	v_mov_b32_e32 v28, v166
	v_mov_b32_e32 v29, v167
	s_nop 0
	v_addc_co_u32_e32 v31, vcc, 0, v59, vcc
	v_add_co_u32_e32 v34, vcc, s43, v58
	v_mov_b32_e32 v30, v168
	v_mov_b32_e32 v31, v169
	v_mov_b32_e32 v32, v170
	v_mov_b32_e32 v33, v171
	s_nop 0
	v_addc_co_u32_e32 v35, vcc, 0, v59, vcc
	v_add_co_u32_e32 v38, vcc, s44, v58
	v_mov_b32_e32 v34, v172
	v_mov_b32_e32 v35, v173
	v_mov_b32_e32 v36, v174
	v_mov_b32_e32 v37, v175
	s_nop 0
	v_addc_co_u32_e32 v39, vcc, 0, v59, vcc
	v_add_co_u32_e32 v42, vcc, s45, v58
	v_mov_b32_e32 v38, v180
	v_mov_b32_e32 v39, v181
	v_mov_b32_e32 v40, v182
	v_mov_b32_e32 v41, v183
	s_nop 0
	v_addc_co_u32_e32 v43, vcc, 0, v59, vcc
	v_add_co_u32_e32 v46, vcc, s46, v58
	v_mov_b32_e32 v42, v184
	v_mov_b32_e32 v43, v185
	v_mov_b32_e32 v44, v186
	v_mov_b32_e32 v45, v187
	s_nop 0
	v_addc_co_u32_e32 v47, vcc, 0, v59, vcc
	v_add_co_u32_e32 v50, vcc, s47, v58
	v_mov_b32_e32 v46, v188
	v_mov_b32_e32 v47, v189
	v_mov_b32_e32 v48, v190
	v_mov_b32_e32 v49, v191
	s_nop 0
	v_addc_co_u32_e32 v51, vcc, 0, v59, vcc
	v_mov_b32_e32 v50, v196
	v_mov_b32_e32 v51, v197
	v_mov_b32_e32 v52, v198
	v_mov_b32_e32 v53, v199
	v_add_u32_e32 v109, 0x428, v103
	v_add_u32_e32 v110, 0x840, v103
	v_add_u32_e32 v111, 0x848, v103
	s_ashr_i32 s14, s14, 2
	s_and_b32 s17, s15, 0x60
	s_ashr_i32 s15, s14, 31
	s_ashr_i32 s16, s6, 31
	s_lshl_b64 s[14:15], s[14:15], 5
	s_add_u32 s6, s14, s6
	s_addc_u32 s14, s15, s16
	s_mul_i32 s16, s14, 0x3000
	s_mul_hi_u32 s14, s6, 0x3000
	s_add_i32 s15, s14, s16
	s_mul_i32 s14, s6, 0x3000
	v_pk_mul_f32 v[2:3], v[2:3], s[8:9] op_sel_hi:[1,0]
	ds_write2_b32 v103, v2, v3 offset1:1
	v_add_co_u32_e32 v2, vcc, s48, v58
	v_pk_mul_f32 v[60:61], v[4:5], s[8:9] op_sel_hi:[1,0]
	s_nop 0
	v_addc_co_u32_e32 v3, vcc, 0, v59, vcc
	v_mov_b32_e32 v2, v200
	v_mov_b32_e32 v3, v201
	v_mov_b32_e32 v4, v202
	v_mov_b32_e32 v5, v203
	v_pk_mul_f32 v[62:63], v[6:7], s[8:9] op_sel_hi:[1,0]
	v_add_co_u32_e32 v6, vcc, s49, v58
	v_pk_mul_f32 v[64:65], v[8:9], s[8:9] op_sel_hi:[1,0]
	s_nop 0
	v_addc_co_u32_e32 v7, vcc, 0, v59, vcc
	v_mov_b32_e32 v54, v204
	v_mov_b32_e32 v55, v205
	v_mov_b32_e32 v56, v206
	v_mov_b32_e32 v57, v207
	v_add_co_u32_e32 v6, vcc, s50, v58
	v_pk_mul_f32 v[10:11], v[10:11], s[8:9] op_sel_hi:[1,0]
	v_addc_co_u32_e32 v7, vcc, 0, v59, vcc
	v_mov_b32_e32 v6, v208
	v_mov_b32_e32 v7, v209
	v_mov_b32_e32 v8, v210
	v_mov_b32_e32 v9, v211
	v_pk_mul_f32 v[12:13], v[12:13], s[8:9] op_sel_hi:[1,0]
	ds_write2_b32 v108, v62, v63 offset1:1
	ds_write2_b32 v109, v64, v65 offset1:1
	ds_write2_b32 v110, v10, v11 offset1:1
	ds_write2_b32 v111, v12, v13 offset1:1
	v_pk_mul_f32 v[10:11], v[14:15], s[8:9] op_sel_hi:[1,0]
	v_add_u32_e32 v12, 0xc60, v103
	ds_write2_b32 v12, v10, v11 offset1:1
	ds_write2_b32 v103, v60, v61 offset0:2 offset1:3
	v_pk_mul_f32 v[10:11], v[16:17], s[8:9] op_sel_hi:[1,0]
	v_add_u32_e32 v12, 0xc68, v103
	ds_write2_b32 v12, v10, v11 offset1:1
	v_pk_mul_f32 v[10:11], v[18:19], s[8:9] op_sel_hi:[1,0]
	v_add_u32_e32 v12, 0x1080, v103
	ds_write2_b32 v12, v10, v11 offset1:1
	v_pk_mul_f32 v[10:11], v[20:21], s[8:9] op_sel_hi:[1,0]
	v_add_u32_e32 v12, 0x1088, v103
	ds_write2_b32 v12, v10, v11 offset1:1
	v_pk_mul_f32 v[10:11], v[22:23], s[8:9] op_sel_hi:[1,0]
	v_add_u32_e32 v12, 0x14a0, v103
	ds_write2_b32 v12, v10, v11 offset1:1
	v_pk_mul_f32 v[10:11], v[24:25], s[8:9] op_sel_hi:[1,0]
	v_add_u32_e32 v12, 0x14a8, v103
	ds_write2_b32 v12, v10, v11 offset1:1
	v_pk_mul_f32 v[10:11], v[26:27], s[8:9] op_sel_hi:[1,0]
	v_add_u32_e32 v12, 0x18c0, v103
	ds_write2_b32 v12, v10, v11 offset1:1
	v_pk_mul_f32 v[10:11], v[28:29], s[8:9] op_sel_hi:[1,0]
	v_add_u32_e32 v12, 0x18c8, v103
	ds_write2_b32 v12, v10, v11 offset1:1
	v_pk_mul_f32 v[10:11], v[30:31], s[8:9] op_sel_hi:[1,0]
	v_add_u32_e32 v12, 0x1ce0, v103
	ds_write2_b32 v12, v10, v11 offset1:1
	v_pk_mul_f32 v[10:11], v[32:33], s[8:9] op_sel_hi:[1,0]
	v_add_u32_e32 v12, 0x1ce8, v103
	ds_write2_b32 v12, v10, v11 offset1:1
	v_pk_mul_f32 v[10:11], v[34:35], s[8:9] op_sel_hi:[1,0]
	v_add_u32_e32 v12, 0x2100, v103
	ds_write2_b32 v12, v10, v11 offset1:1
	v_pk_mul_f32 v[10:11], v[36:37], s[8:9] op_sel_hi:[1,0]
	v_add_u32_e32 v12, 0x2108, v103
	ds_write2_b32 v12, v10, v11 offset1:1
	v_pk_mul_f32 v[10:11], v[38:39], s[8:9] op_sel_hi:[1,0]
	v_add_u32_e32 v12, 0x2520, v103
	ds_write2_b32 v12, v10, v11 offset1:1
	v_pk_mul_f32 v[10:11], v[40:41], s[8:9] op_sel_hi:[1,0]
	v_add_u32_e32 v12, 0x2528, v103
	ds_write2_b32 v12, v10, v11 offset1:1
	v_pk_mul_f32 v[10:11], v[42:43], s[8:9] op_sel_hi:[1,0]
	v_add_u32_e32 v12, 0x2940, v103
	ds_write2_b32 v12, v10, v11 offset1:1
	v_pk_mul_f32 v[10:11], v[44:45], s[8:9] op_sel_hi:[1,0]
	v_add_u32_e32 v12, 0x2948, v103
	ds_write2_b32 v12, v10, v11 offset1:1
	v_pk_mul_f32 v[10:11], v[46:47], s[8:9] op_sel_hi:[1,0]
	v_add_u32_e32 v12, 0x2d60, v103
	ds_write2_b32 v12, v10, v11 offset1:1
	v_pk_mul_f32 v[10:11], v[48:49], s[8:9] op_sel_hi:[1,0]
	v_add_u32_e32 v12, 0x2d68, v103
	ds_write2_b32 v12, v10, v11 offset1:1
	v_pk_mul_f32 v[10:11], v[50:51], s[8:9] op_sel_hi:[1,0]
	v_add_u32_e32 v12, 0x3180, v103
	ds_write2_b32 v12, v10, v11 offset1:1
	v_pk_mul_f32 v[10:11], v[52:53], s[8:9] op_sel_hi:[1,0]
	v_add_u32_e32 v12, 0x3188, v103
	ds_write2_b32 v12, v10, v11 offset1:1
	v_add_u32_e32 v10, 0x35a0, v103
	v_add_u32_e32 v45, 0x400, v86
	v_add_u32_e32 v53, 0x800, v86
	v_add_u32_e32 v24, 0xa00, v86
	v_pk_mul_f32 v[2:3], v[2:3], s[8:9] op_sel_hi:[1,0]
	ds_write2_b32 v10, v2, v3 offset1:1
	v_pk_mul_f32 v[2:3], v[4:5], s[8:9] op_sel_hi:[1,0]
	v_add_u32_e32 v4, 0x35a8, v103
	ds_write2_b32 v4, v2, v3 offset1:1
	v_add_u32_e32 v4, 0x39c0, v103
	v_add_u32_e32 v60, 0xc00, v86
	v_pk_mul_f32 v[2:3], v[54:55], s[8:9] op_sel_hi:[1,0]
	ds_write2_b32 v4, v2, v3 offset1:1
	v_pk_mul_f32 v[2:3], v[56:57], s[8:9] op_sel_hi:[1,0]
	v_add_u32_e32 v4, 0x39c8, v103
	ds_write2_b32 v4, v2, v3 offset1:1
	v_add_u32_e32 v4, 0x3de0, v103
	s_branch .Lpf_join
